# G5 SwiGLU epilogue start: vmcnt(0) -> vmcnt(8) (the row-scale loads it guards are 32 K-iterations old; the next tile's LDS-DMA prefetch may stay in flight)
# speedup vs baseline: 1.0024x; 1.0017x over previous
.LBB0_1801:
	s_waitcnt vmcnt(8)
	v_pk_mul_f32 v[126:127], v[158:159], v[126:127] op_sel_hi:[0,1]
	v_pk_mul_f32 v[164:165], v[158:159], v[116:117] op_sel_hi:[0,1]
	v_pk_mul_f32 v[116:117], v[158:159], v[114:115] op_sel_hi:[0,1]
	v_mul_f32_e32 v114, 0xbfb8aa3b, v126
	v_exp_f32_e32 v114, v114
	v_pk_mul_f32 v[118:119], v[158:159], v[118:119] op_sel_hi:[0,1]
	v_mul_f32_e32 v115, v126, v118
	v_mul_f32_e32 v118, v127, v119
	v_add_f32_e32 v114, 1.0, v114
	v_rcp_f32_e32 v114, v114
	v_pk_mul_f32 v[128:129], v[158:159], v[128:129] op_sel_hi:[0,1]
	v_pk_mul_f32 v[120:121], v[158:159], v[120:121] op_sel_hi:[0,1]
	v_mul_f32_e32 v119, v129, v121
	v_mul_f32_e32 v114, v114, v115
	v_mul_f32_e32 v115, 0xbfb8aa3b, v127
	v_exp_f32_e32 v115, v115
	v_pk_mul_f32 v[122:123], v[158:159], v[122:123] op_sel_hi:[0,1]
	v_mul_f32_e32 v116, v122, v116
	v_mul_f32_e32 v117, v123, v117
	v_add_f32_e32 v115, 1.0, v115
	v_rcp_f32_e32 v115, v115
	v_pk_mul_f32 v[124:125], v[158:159], v[124:125] op_sel_hi:[0,1]
	v_lshl_add_u32 v147, s9, 8, v1
	v_lshl_or_b32 v154, s8, 7, v143
	v_mul_f32_e32 v115, v115, v118
	v_cvt_pk_bf16_f32 v114, v114, v115
	v_mul_f32_e32 v115, 0xbfb8aa3b, v128
	v_exp_f32_e32 v115, v115
	v_mul_f32_e32 v118, v128, v120
	v_readlane_b32 s8, v245, 21
	v_readlane_b32 s9, v245, 22
	v_add_f32_e32 v115, 1.0, v115
	v_rcp_f32_e32 v115, v115
	v_ashrrev_i32_e32 v155, 31, v154
	v_mov_b64_e32 v[152:153], s[8:9]
	s_movk_i32 s5, 0x2c00
	v_mul_f32_e32 v115, v115, v118
	v_mul_f32_e32 v118, 0xbfb8aa3b, v129
	v_exp_f32_e32 v118, v118
	v_mad_i64_i32 v[160:161], s[8:9], v147, s5, v[152:153]
	v_lshlrev_b64 v[154:155], 1, v[154:155]
	v_add_f32_e32 v118, 1.0, v118
	v_rcp_f32_e32 v118, v118
	v_lshl_add_u64 v[160:161], v[160:161], 0, v[154:155]
	v_pk_mul_f32 v[110:111], v[156:157], v[110:111] op_sel_hi:[0,1]
	v_pk_mul_f32 v[102:103], v[156:157], v[102:103] op_sel_hi:[0,1]
	v_mul_f32_e32 v118, v118, v119
	v_cvt_pk_bf16_f32 v115, v115, v118
	v_mul_f32_e32 v118, 0xbfb8aa3b, v122
	v_exp_f32_e32 v118, v118
	v_mul_f32_e32 v119, v125, v165
	v_pk_mul_f32 v[112:113], v[156:157], v[112:113] op_sel_hi:[0,1]
	v_pk_mul_f32 v[104:105], v[156:157], v[104:105] op_sel_hi:[0,1]
	v_add_f32_e32 v118, 1.0, v118
	v_rcp_f32_e32 v118, v118
	v_pk_mul_f32 v[106:107], v[156:157], v[106:107] op_sel_hi:[0,1]
	v_pk_mul_f32 v[108:109], v[156:157], v[108:109] op_sel_hi:[0,1]
	v_pk_mul_f32 v[94:95], v[150:151], v[94:95] op_sel_hi:[0,1]
	v_mul_f32_e32 v116, v118, v116
	v_mul_f32_e32 v118, 0xbfb8aa3b, v123
	v_exp_f32_e32 v118, v118
	v_pk_mul_f32 v[86:87], v[150:151], v[86:87] op_sel_hi:[0,1]
	v_pk_mul_f32 v[96:97], v[150:151], v[96:97] op_sel_hi:[0,1]
	v_pk_mul_f32 v[88:89], v[150:151], v[88:89] op_sel_hi:[0,1]
	v_add_f32_e32 v118, 1.0, v118
	v_rcp_f32_e32 v118, v118
	v_pk_mul_f32 v[90:91], v[150:151], v[90:91] op_sel_hi:[0,1]
	v_pk_mul_f32 v[92:93], v[150:151], v[92:93] op_sel_hi:[0,1]
	v_pk_mul_f32 v[78:79], v[148:149], v[78:79] op_sel_hi:[0,1]
	v_mul_f32_e32 v117, v118, v117
	v_cvt_pk_bf16_f32 v116, v116, v117
	v_mul_f32_e32 v117, 0xbfb8aa3b, v124
	v_exp_f32_e32 v117, v117
	v_mul_f32_e32 v118, v124, v164
	v_pk_mul_f32 v[70:71], v[148:149], v[70:71] op_sel_hi:[0,1]
	v_pk_mul_f32 v[80:81], v[148:149], v[80:81] op_sel_hi:[0,1]
	v_add_f32_e32 v117, 1.0, v117
	v_rcp_f32_e32 v117, v117
	v_pk_mul_f32 v[72:73], v[148:149], v[72:73] op_sel_hi:[0,1]
	v_pk_mul_f32 v[74:75], v[148:149], v[74:75] op_sel_hi:[0,1]
	v_pk_mul_f32 v[76:77], v[148:149], v[76:77] op_sel_hi:[0,1]
	v_mul_f32_e32 v117, v117, v118
	v_mul_f32_e32 v118, 0xbfb8aa3b, v125
	v_exp_f32_e32 v118, v118
	v_pk_mul_f32 v[62:63], v[146:147], v[62:63] op_sel_hi:[0,1]
	v_pk_mul_f32 v[54:55], v[146:147], v[54:55] op_sel_hi:[0,1]
	v_pk_mul_f32 v[64:65], v[146:147], v[64:65] op_sel_hi:[0,1]
	v_add_f32_e32 v118, 1.0, v118
	v_rcp_f32_e32 v118, v118
	v_pk_mul_f32 v[56:57], v[146:147], v[56:57] op_sel_hi:[0,1]
	v_pk_mul_f32 v[58:59], v[146:147], v[58:59] op_sel_hi:[0,1]
	v_pk_mul_f32 v[60:61], v[146:147], v[60:61] op_sel_hi:[0,1]
	v_mul_f32_e32 v118, v118, v119
	v_cvt_pk_bf16_f32 v117, v117, v118
	global_store_dwordx4 v[160:161], v[114:117], off
	v_pk_mul_f32 v[46:47], v[144:145], v[46:47] op_sel_hi:[0,1]
	v_pk_mul_f32 v[38:39], v[144:145], v[38:39] op_sel_hi:[0,1]
	v_pk_mul_f32 v[116:117], v[156:157], v[100:101] op_sel_hi:[0,1]
	v_pk_mul_f32 v[100:101], v[156:157], v[98:99] op_sel_hi:[0,1]
	v_mul_f32_e32 v98, 0xbfb8aa3b, v110
	v_exp_f32_e32 v98, v98
	v_mul_f32_e32 v99, v110, v102
	v_mul_f32_e32 v102, v111, v103
	v_mul_f32_e32 v103, v113, v105
	v_add_f32_e32 v98, 1.0, v98
	v_rcp_f32_e32 v98, v98
	v_mul_f32_e32 v100, v106, v100
	v_mul_f32_e32 v101, v107, v101
	v_or_b32_e32 v114, 16, v147
	v_mul_f32_e32 v98, v98, v99
	v_mul_f32_e32 v99, 0xbfb8aa3b, v111
	v_exp_f32_e32 v99, v99
	v_mad_i64_i32 v[114:115], s[8:9], v114, s5, v[152:153]
	v_lshl_add_u64 v[114:115], v[114:115], 0, v[154:155]
	v_add_f32_e32 v99, 1.0, v99
	v_rcp_f32_e32 v99, v99
	v_pk_mul_f32 v[48:49], v[144:145], v[48:49] op_sel_hi:[0,1]
	v_pk_mul_f32 v[40:41], v[144:145], v[40:41] op_sel_hi:[0,1]
	v_pk_mul_f32 v[42:43], v[144:145], v[42:43] op_sel_hi:[0,1]
	v_mul_f32_e32 v99, v99, v102
	v_cvt_pk_bf16_f32 v98, v98, v99
	v_mul_f32_e32 v99, 0xbfb8aa3b, v112
	v_exp_f32_e32 v99, v99
	v_mul_f32_e32 v102, v112, v104
	v_pk_mul_f32 v[44:45], v[144:145], v[44:45] op_sel_hi:[0,1]
	v_pk_mul_f32 v[30:31], v[142:143], v[30:31] op_sel_hi:[0,1]
	v_add_f32_e32 v99, 1.0, v99
	v_rcp_f32_e32 v99, v99
	v_pk_mul_f32 v[22:23], v[142:143], v[22:23] op_sel_hi:[0,1]
	v_pk_mul_f32 v[32:33], v[142:143], v[32:33] op_sel_hi:[0,1]
	v_pk_mul_f32 v[24:25], v[142:143], v[24:25] op_sel_hi:[0,1]
	v_mul_f32_e32 v99, v99, v102
	v_mul_f32_e32 v102, 0xbfb8aa3b, v113
	v_exp_f32_e32 v102, v102
	v_pk_mul_f32 v[26:27], v[142:143], v[26:27] op_sel_hi:[0,1]
	v_pk_mul_f32 v[28:29], v[142:143], v[28:29] op_sel_hi:[0,1]
	v_pk_mul_f32 v[14:15], v[140:141], v[14:15] op_sel_hi:[0,1]
	v_add_f32_e32 v102, 1.0, v102
	v_rcp_f32_e32 v102, v102
	v_pk_mul_f32 v[6:7], v[140:141], v[6:7] op_sel_hi:[0,1]
	v_pk_mul_f32 v[16:17], v[140:141], v[16:17] op_sel_hi:[0,1]
	v_pk_mul_f32 v[8:9], v[140:141], v[8:9] op_sel_hi:[0,1]
	v_mul_f32_e32 v102, v102, v103
	v_cvt_pk_bf16_f32 v99, v99, v102
	v_mul_f32_e32 v102, 0xbfb8aa3b, v106
	v_exp_f32_e32 v102, v102
	v_mul_f32_e32 v103, v109, v117
	v_pk_mul_f32 v[10:11], v[140:141], v[10:11] op_sel_hi:[0,1]
	v_pk_mul_f32 v[12:13], v[140:141], v[12:13] op_sel_hi:[0,1]
	v_add_f32_e32 v102, 1.0, v102
	v_rcp_f32_e32 v102, v102
	s_mov_b64 s[22:23], -1
	s_andn2_b64 vcc, exec, s[34:35]
	s_mov_b32 s26, 0x2aaaaaab
	v_mul_f32_e32 v100, v102, v100
	v_mul_f32_e32 v102, 0xbfb8aa3b, v107
	v_exp_f32_e32 v102, v102
	s_nop 0
	v_add_f32_e32 v102, 1.0, v102
	v_rcp_f32_e32 v102, v102
	s_nop 0
	v_mul_f32_e32 v101, v102, v101
	v_cvt_pk_bf16_f32 v100, v100, v101
	v_mul_f32_e32 v101, 0xbfb8aa3b, v108
	v_exp_f32_e32 v101, v101
	v_mul_f32_e32 v102, v108, v116
	v_add_f32_e32 v101, 1.0, v101
	v_rcp_f32_e32 v101, v101
	s_nop 0
	v_mul_f32_e32 v101, v101, v102
	v_mul_f32_e32 v102, 0xbfb8aa3b, v109
	v_exp_f32_e32 v102, v102
	s_nop 0
	v_add_f32_e32 v102, 1.0, v102
	v_rcp_f32_e32 v102, v102
	s_nop 0
	v_mul_f32_e32 v102, v102, v103
	v_cvt_pk_bf16_f32 v101, v101, v102
	global_store_dwordx4 v[114:115], v[98:101], off
	s_nop 1
	v_pk_mul_f32 v[100:101], v[150:151], v[84:85] op_sel_hi:[0,1]
	v_pk_mul_f32 v[84:85], v[150:151], v[82:83] op_sel_hi:[0,1]
	v_mul_f32_e32 v82, 0xbfb8aa3b, v94
	v_exp_f32_e32 v82, v82
	v_mul_f32_e32 v83, v94, v86
	v_mul_f32_e32 v86, v95, v87
	v_mul_f32_e32 v87, v97, v89
	v_add_f32_e32 v82, 1.0, v82
	v_rcp_f32_e32 v82, v82
	v_mul_f32_e32 v84, v90, v84
	v_mul_f32_e32 v85, v91, v85
	v_or_b32_e32 v98, 32, v147
	v_mul_f32_e32 v82, v82, v83
	v_mul_f32_e32 v83, 0xbfb8aa3b, v95
	v_exp_f32_e32 v83, v83
	v_mad_i64_i32 v[98:99], s[8:9], v98, s5, v[152:153]
	v_lshl_add_u64 v[98:99], v[98:99], 0, v[154:155]
	v_add_f32_e32 v83, 1.0, v83
	v_rcp_f32_e32 v83, v83
	s_nop 0
	v_mul_f32_e32 v83, v83, v86
	v_cvt_pk_bf16_f32 v82, v82, v83
	v_mul_f32_e32 v83, 0xbfb8aa3b, v96
	v_exp_f32_e32 v83, v83
	v_mul_f32_e32 v86, v96, v88
	v_add_f32_e32 v83, 1.0, v83
	v_rcp_f32_e32 v83, v83
	s_nop 0
	v_mul_f32_e32 v83, v83, v86
	v_mul_f32_e32 v86, 0xbfb8aa3b, v97
	v_exp_f32_e32 v86, v86
	s_nop 0
	v_add_f32_e32 v86, 1.0, v86
	v_rcp_f32_e32 v86, v86
	s_nop 0
	v_mul_f32_e32 v86, v86, v87
	v_cvt_pk_bf16_f32 v83, v83, v86
	v_mul_f32_e32 v86, 0xbfb8aa3b, v90
	v_exp_f32_e32 v86, v86
	v_mul_f32_e32 v87, v93, v101
	v_add_f32_e32 v86, 1.0, v86
	v_rcp_f32_e32 v86, v86
	s_nop 0
	v_mul_f32_e32 v84, v86, v84
	v_mul_f32_e32 v86, 0xbfb8aa3b, v91
	v_exp_f32_e32 v86, v86
	s_nop 0
	v_add_f32_e32 v86, 1.0, v86
	v_rcp_f32_e32 v86, v86
	s_nop 0
	v_mul_f32_e32 v85, v86, v85
	v_cvt_pk_bf16_f32 v84, v84, v85
	v_mul_f32_e32 v85, 0xbfb8aa3b, v92
	v_exp_f32_e32 v85, v85
	v_mul_f32_e32 v86, v92, v100
	v_add_f32_e32 v85, 1.0, v85
	v_rcp_f32_e32 v85, v85
	s_nop 0
	v_mul_f32_e32 v85, v85, v86
	v_mul_f32_e32 v86, 0xbfb8aa3b, v93
	v_exp_f32_e32 v86, v86
	s_nop 0
	v_add_f32_e32 v86, 1.0, v86
	v_rcp_f32_e32 v86, v86
	s_nop 0
	v_mul_f32_e32 v86, v86, v87
	v_cvt_pk_bf16_f32 v85, v85, v86
	global_store_dwordx4 v[98:99], v[82:85], off
	s_nop 1
	v_pk_mul_f32 v[84:85], v[148:149], v[68:69] op_sel_hi:[0,1]
	v_pk_mul_f32 v[68:69], v[148:149], v[66:67] op_sel_hi:[0,1]
	v_mul_f32_e32 v66, 0xbfb8aa3b, v78
	v_exp_f32_e32 v66, v66
	v_mul_f32_e32 v67, v78, v70
	v_mul_f32_e32 v70, v79, v71
	v_mul_f32_e32 v71, v81, v73
	v_add_f32_e32 v66, 1.0, v66
	v_rcp_f32_e32 v66, v66
	v_mul_f32_e32 v68, v74, v68
	v_mul_f32_e32 v69, v75, v69
	v_or_b32_e32 v82, 48, v147
	v_mul_f32_e32 v66, v66, v67
	v_mul_f32_e32 v67, 0xbfb8aa3b, v79
	v_exp_f32_e32 v67, v67
	v_mad_i64_i32 v[82:83], s[8:9], v82, s5, v[152:153]
	v_lshl_add_u64 v[82:83], v[82:83], 0, v[154:155]
	v_add_f32_e32 v67, 1.0, v67
	v_rcp_f32_e32 v67, v67
	s_nop 0
	v_mul_f32_e32 v67, v67, v70
	v_cvt_pk_bf16_f32 v66, v66, v67
	v_mul_f32_e32 v67, 0xbfb8aa3b, v80
	v_exp_f32_e32 v67, v67
	v_mul_f32_e32 v70, v80, v72
	v_add_f32_e32 v67, 1.0, v67
	v_rcp_f32_e32 v67, v67
	s_nop 0
	v_mul_f32_e32 v67, v67, v70
	v_mul_f32_e32 v70, 0xbfb8aa3b, v81
	v_exp_f32_e32 v70, v70
	s_nop 0
	v_add_f32_e32 v70, 1.0, v70
	v_rcp_f32_e32 v70, v70
	s_nop 0
	v_mul_f32_e32 v70, v70, v71
	v_cvt_pk_bf16_f32 v67, v67, v70
	v_mul_f32_e32 v70, 0xbfb8aa3b, v74
	v_exp_f32_e32 v70, v70
	v_mul_f32_e32 v71, v77, v85
	v_add_f32_e32 v70, 1.0, v70
	v_rcp_f32_e32 v70, v70
	s_nop 0
	v_mul_f32_e32 v68, v70, v68
	v_mul_f32_e32 v70, 0xbfb8aa3b, v75
	v_exp_f32_e32 v70, v70
	s_nop 0
	v_add_f32_e32 v70, 1.0, v70
	v_rcp_f32_e32 v70, v70
	s_nop 0
	v_mul_f32_e32 v69, v70, v69
	v_cvt_pk_bf16_f32 v68, v68, v69
	v_mul_f32_e32 v69, 0xbfb8aa3b, v76
	v_exp_f32_e32 v69, v69
	v_mul_f32_e32 v70, v76, v84
	v_add_f32_e32 v69, 1.0, v69
	v_rcp_f32_e32 v69, v69
	s_nop 0
	v_mul_f32_e32 v69, v69, v70
	v_mul_f32_e32 v70, 0xbfb8aa3b, v77
	v_exp_f32_e32 v70, v70
	s_nop 0
	v_add_f32_e32 v70, 1.0, v70
	v_rcp_f32_e32 v70, v70
	s_nop 0
	v_mul_f32_e32 v70, v70, v71
	v_cvt_pk_bf16_f32 v69, v69, v70
	global_store_dwordx4 v[82:83], v[66:69], off
	s_nop 1
	v_pk_mul_f32 v[68:69], v[146:147], v[52:53] op_sel_hi:[0,1]
	v_pk_mul_f32 v[52:53], v[146:147], v[50:51] op_sel_hi:[0,1]
	v_mul_f32_e32 v50, 0xbfb8aa3b, v62
	v_exp_f32_e32 v50, v50
	v_mul_f32_e32 v51, v62, v54
	v_mul_f32_e32 v54, v63, v55
	v_mul_f32_e32 v55, v65, v57
	v_add_f32_e32 v50, 1.0, v50
	v_rcp_f32_e32 v50, v50
	v_mul_f32_e32 v52, v58, v52
	v_mul_f32_e32 v53, v59, v53
	v_add_u32_e32 v66, 0x80, v147
	v_mul_f32_e32 v50, v50, v51
	v_mul_f32_e32 v51, 0xbfb8aa3b, v63
	v_exp_f32_e32 v51, v51
	v_mad_i64_i32 v[66:67], s[8:9], v66, s5, v[152:153]
	v_lshl_add_u64 v[66:67], v[66:67], 0, v[154:155]
	v_add_f32_e32 v51, 1.0, v51
	v_rcp_f32_e32 v51, v51
	s_nop 0
	v_mul_f32_e32 v51, v51, v54
	v_cvt_pk_bf16_f32 v50, v50, v51
	v_mul_f32_e32 v51, 0xbfb8aa3b, v64
	v_exp_f32_e32 v51, v51
	v_mul_f32_e32 v54, v64, v56
	v_add_f32_e32 v51, 1.0, v51
	v_rcp_f32_e32 v51, v51
	s_nop 0
	v_mul_f32_e32 v51, v51, v54
	v_mul_f32_e32 v54, 0xbfb8aa3b, v65
	v_exp_f32_e32 v54, v54
	s_nop 0
	v_add_f32_e32 v54, 1.0, v54
	v_rcp_f32_e32 v54, v54
	s_nop 0
	v_mul_f32_e32 v54, v54, v55
	v_cvt_pk_bf16_f32 v51, v51, v54
	v_mul_f32_e32 v54, 0xbfb8aa3b, v58
	v_exp_f32_e32 v54, v54
	v_mul_f32_e32 v55, v61, v69
	v_add_f32_e32 v54, 1.0, v54
	v_rcp_f32_e32 v54, v54
	s_nop 0
	v_mul_f32_e32 v52, v54, v52
	v_mul_f32_e32 v54, 0xbfb8aa3b, v59
	v_exp_f32_e32 v54, v54
	s_nop 0
	v_add_f32_e32 v54, 1.0, v54
	v_rcp_f32_e32 v54, v54
	s_nop 0
	v_mul_f32_e32 v53, v54, v53
	v_cvt_pk_bf16_f32 v52, v52, v53
	v_mul_f32_e32 v53, 0xbfb8aa3b, v60
	v_exp_f32_e32 v53, v53
	v_mul_f32_e32 v54, v60, v68
	v_add_f32_e32 v53, 1.0, v53
	v_rcp_f32_e32 v53, v53
	s_nop 0
	v_mul_f32_e32 v53, v53, v54
	v_mul_f32_e32 v54, 0xbfb8aa3b, v61
	v_exp_f32_e32 v54, v54
	s_nop 0
	v_add_f32_e32 v54, 1.0, v54
	v_rcp_f32_e32 v54, v54
	s_nop 0
	v_mul_f32_e32 v54, v54, v55
	v_cvt_pk_bf16_f32 v53, v53, v54
	global_store_dwordx4 v[66:67], v[50:53], off
	s_nop 1
	v_pk_mul_f32 v[52:53], v[144:145], v[36:37] op_sel_hi:[0,1]
	v_pk_mul_f32 v[36:37], v[144:145], v[34:35] op_sel_hi:[0,1]
	v_mul_f32_e32 v34, 0xbfb8aa3b, v46
	v_exp_f32_e32 v34, v34
	v_mul_f32_e32 v35, v46, v38
	v_mul_f32_e32 v38, v47, v39
	v_mul_f32_e32 v39, v49, v41
	v_add_f32_e32 v34, 1.0, v34
	v_rcp_f32_e32 v34, v34
	v_mul_f32_e32 v36, v42, v36
	v_mul_f32_e32 v37, v43, v37
	v_add_u32_e32 v50, 0x90, v147
	v_mul_f32_e32 v34, v34, v35
	v_mul_f32_e32 v35, 0xbfb8aa3b, v47
	v_exp_f32_e32 v35, v35
	v_mad_i64_i32 v[50:51], s[8:9], v50, s5, v[152:153]
	v_lshl_add_u64 v[50:51], v[50:51], 0, v[154:155]
	v_add_f32_e32 v35, 1.0, v35
	v_rcp_f32_e32 v35, v35
	s_nop 0
	v_mul_f32_e32 v35, v35, v38
	v_cvt_pk_bf16_f32 v34, v34, v35
	v_mul_f32_e32 v35, 0xbfb8aa3b, v48
	v_exp_f32_e32 v35, v35
	v_mul_f32_e32 v38, v48, v40
	v_add_f32_e32 v35, 1.0, v35
	v_rcp_f32_e32 v35, v35
	s_nop 0
	v_mul_f32_e32 v35, v35, v38
	v_mul_f32_e32 v38, 0xbfb8aa3b, v49
	v_exp_f32_e32 v38, v38
	s_nop 0
	v_add_f32_e32 v38, 1.0, v38
	v_rcp_f32_e32 v38, v38
	s_nop 0
	v_mul_f32_e32 v38, v38, v39
	v_cvt_pk_bf16_f32 v35, v35, v38
	v_mul_f32_e32 v38, 0xbfb8aa3b, v42
	v_exp_f32_e32 v38, v38
	v_mul_f32_e32 v39, v45, v53
	v_add_f32_e32 v38, 1.0, v38
	v_rcp_f32_e32 v38, v38
	s_nop 0
	v_mul_f32_e32 v36, v38, v36
	v_mul_f32_e32 v38, 0xbfb8aa3b, v43
	v_exp_f32_e32 v38, v38
	s_nop 0
	v_add_f32_e32 v38, 1.0, v38
	v_rcp_f32_e32 v38, v38
	s_nop 0
	v_mul_f32_e32 v37, v38, v37
	v_cvt_pk_bf16_f32 v36, v36, v37
	v_mul_f32_e32 v37, 0xbfb8aa3b, v44
	v_exp_f32_e32 v37, v37
	v_mul_f32_e32 v38, v44, v52
	v_add_f32_e32 v37, 1.0, v37
	v_rcp_f32_e32 v37, v37
	s_nop 0
	v_mul_f32_e32 v37, v37, v38
	v_mul_f32_e32 v38, 0xbfb8aa3b, v45
	v_exp_f32_e32 v38, v38
	s_nop 0
	v_add_f32_e32 v38, 1.0, v38
	v_rcp_f32_e32 v38, v38
	s_nop 0
	v_mul_f32_e32 v38, v38, v39
	v_cvt_pk_bf16_f32 v37, v37, v38
	global_store_dwordx4 v[50:51], v[34:37], off
	s_nop 1
	v_pk_mul_f32 v[36:37], v[142:143], v[20:21] op_sel_hi:[0,1]
	v_pk_mul_f32 v[20:21], v[142:143], v[18:19] op_sel_hi:[0,1]
	v_mul_f32_e32 v18, 0xbfb8aa3b, v30
	v_exp_f32_e32 v18, v18
	v_mul_f32_e32 v19, v30, v22
	v_mul_f32_e32 v22, v31, v23
	v_mul_f32_e32 v23, v33, v25
	v_add_f32_e32 v18, 1.0, v18
	v_rcp_f32_e32 v18, v18
	v_mul_f32_e32 v20, v26, v20
	v_mul_f32_e32 v21, v27, v21
	v_add_u32_e32 v34, 0xa0, v147
	v_mul_f32_e32 v18, v18, v19
	v_mul_f32_e32 v19, 0xbfb8aa3b, v31
	v_exp_f32_e32 v19, v19
	v_mad_i64_i32 v[34:35], s[8:9], v34, s5, v[152:153]
	v_lshl_add_u64 v[34:35], v[34:35], 0, v[154:155]
	v_add_f32_e32 v19, 1.0, v19
	v_rcp_f32_e32 v19, v19
	s_nop 0
	v_mul_f32_e32 v19, v19, v22
	v_cvt_pk_bf16_f32 v18, v18, v19
	v_mul_f32_e32 v19, 0xbfb8aa3b, v32
	v_exp_f32_e32 v19, v19
	v_mul_f32_e32 v22, v32, v24
	v_add_f32_e32 v19, 1.0, v19
	v_rcp_f32_e32 v19, v19
	s_nop 0
	v_mul_f32_e32 v19, v19, v22
	v_mul_f32_e32 v22, 0xbfb8aa3b, v33
	v_exp_f32_e32 v22, v22
	s_nop 0
	v_add_f32_e32 v22, 1.0, v22
	v_rcp_f32_e32 v22, v22
	s_nop 0
	v_mul_f32_e32 v22, v22, v23
	v_cvt_pk_bf16_f32 v19, v19, v22
	v_mul_f32_e32 v22, 0xbfb8aa3b, v26
	v_exp_f32_e32 v22, v22
	v_mul_f32_e32 v23, v29, v37
	v_add_f32_e32 v22, 1.0, v22
	v_rcp_f32_e32 v22, v22
	s_nop 0
	v_mul_f32_e32 v20, v22, v20
	v_mul_f32_e32 v22, 0xbfb8aa3b, v27
	v_exp_f32_e32 v22, v22
	s_nop 0
	v_add_f32_e32 v22, 1.0, v22
	v_rcp_f32_e32 v22, v22
	s_nop 0
	v_mul_f32_e32 v21, v22, v21
	v_cvt_pk_bf16_f32 v20, v20, v21
	v_mul_f32_e32 v21, 0xbfb8aa3b, v28
	v_exp_f32_e32 v21, v21
	v_mul_f32_e32 v22, v28, v36
	v_add_f32_e32 v21, 1.0, v21
	v_rcp_f32_e32 v21, v21
	s_nop 0
	v_mul_f32_e32 v21, v21, v22
	v_mul_f32_e32 v22, 0xbfb8aa3b, v29
	v_exp_f32_e32 v22, v22
	s_nop 0
	v_add_f32_e32 v22, 1.0, v22
	v_rcp_f32_e32 v22, v22
	s_nop 0
	v_mul_f32_e32 v22, v22, v23
	v_cvt_pk_bf16_f32 v21, v21, v22
	global_store_dwordx4 v[34:35], v[18:21], off
	s_nop 1
	v_pk_mul_f32 v[20:21], v[140:141], v[4:5] op_sel_hi:[0,1]
	v_pk_mul_f32 v[4:5], v[140:141], v[2:3] op_sel_hi:[0,1]
	v_mul_f32_e32 v2, 0xbfb8aa3b, v14
	v_exp_f32_e32 v2, v2
	v_mul_f32_e32 v3, v14, v6
	v_mul_f32_e32 v6, v15, v7
	v_mul_f32_e32 v7, v17, v9
	v_add_f32_e32 v2, 1.0, v2
	v_rcp_f32_e32 v2, v2
	v_mul_f32_e32 v4, v10, v4
	v_mul_f32_e32 v5, v11, v5
	v_add_u32_e32 v18, 0xb0, v147
	v_mul_f32_e32 v2, v2, v3
	v_mul_f32_e32 v3, 0xbfb8aa3b, v15
	v_exp_f32_e32 v3, v3
	v_mad_i64_i32 v[18:19], s[8:9], v18, s5, v[152:153]
	v_lshl_add_u64 v[18:19], v[18:19], 0, v[154:155]
	v_add_f32_e32 v3, 1.0, v3
	v_rcp_f32_e32 v3, v3
	s_nop 0
	v_mul_f32_e32 v3, v3, v6
	v_cvt_pk_bf16_f32 v2, v2, v3
	v_mul_f32_e32 v3, 0xbfb8aa3b, v16
	v_exp_f32_e32 v3, v3
	v_mul_f32_e32 v6, v16, v8
	v_add_f32_e32 v3, 1.0, v3
	v_rcp_f32_e32 v3, v3
	s_nop 0
	v_mul_f32_e32 v3, v3, v6
	v_mul_f32_e32 v6, 0xbfb8aa3b, v17
	v_exp_f32_e32 v6, v6
	s_nop 0
	v_add_f32_e32 v6, 1.0, v6
	v_rcp_f32_e32 v6, v6
	s_nop 0
	v_mul_f32_e32 v6, v6, v7
	v_cvt_pk_bf16_f32 v3, v3, v6
	v_mul_f32_e32 v6, 0xbfb8aa3b, v10
	v_exp_f32_e32 v6, v6
	v_mul_f32_e32 v7, v13, v21
	v_add_f32_e32 v6, 1.0, v6
	v_rcp_f32_e32 v6, v6
	s_nop 0
	v_mul_f32_e32 v4, v6, v4
	v_mul_f32_e32 v6, 0xbfb8aa3b, v11
	v_exp_f32_e32 v6, v6
	s_nop 0
	v_add_f32_e32 v6, 1.0, v6
	v_rcp_f32_e32 v6, v6
	s_nop 0
	v_mul_f32_e32 v5, v6, v5
	v_cvt_pk_bf16_f32 v4, v4, v5
	v_mul_f32_e32 v5, 0xbfb8aa3b, v12
	v_exp_f32_e32 v5, v5
	v_mul_f32_e32 v6, v12, v20
	v_add_f32_e32 v5, 1.0, v5
	v_rcp_f32_e32 v5, v5
	s_nop 0
	v_mul_f32_e32 v5, v5, v6
	v_mul_f32_e32 v6, 0xbfb8aa3b, v13
	v_exp_f32_e32 v6, v6
	s_nop 0
	v_add_f32_e32 v6, 1.0, v6
	v_rcp_f32_e32 v6, v6
	s_nop 0
	v_mul_f32_e32 v6, v6, v7
	v_cvt_pk_bf16_f32 v5, v5, v6
	global_store_dwordx4 v[18:19], v[2:5], off
	s_cbranch_vccnz .LBB0_1794
	s_nop 0
	v_lshl_add_u32 v2, s18, 8, v1
	v_readlane_b32 s8, v245, 16
	v_ashrrev_i32_e32 v3, 31, v2
	v_readlane_b32 s9, v245, 17
	s_andn2_b64 vcc, exec, s[0:1]
	s_nop 0
	v_lshl_add_u64 v[2:3], v[2:3], 2, s[8:9]
	global_load_dword v158, v[2:3], off
	global_load_dword v156, v[2:3], off offset:64
	global_load_dword v150, v[2:3], off offset:128
	global_load_dword v148, v[2:3], off offset:192
	global_load_dword v146, v[2:3], off offset:512
	global_load_dword v144, v[2:3], off offset:576
	global_load_dword v142, v[2:3], off offset:640
	global_load_dword v140, v[2:3], off offset:704
	s_cbranch_vccnz .LBB0_1793
	s_barrier
	s_branch .LBB0_1793
